# prompt attention: row groups paired so the two waves of a SIMD own 64-row chunks 0+3 or 1+2 of the 256-row block (equal tile counts per SIMD)
# speedup vs baseline: 1.0047x; 1.0047x over previous
; template<int THRL,bool PART> __device__ __forceinline__ int attn_unit(const bf16*Qb,const bf16*__restrict__ Kh,const bf16*__restrict__ Vh,bf16*Ob,const int NT,const int vlim_in,char*shm,const int s0,const bool primed,const bf16*nKh,const bf16*nVh,bf16*fuseM,const float lam){
;   int tid=threadIdx.x; asm volatile("":"+v"(tid));
;   const int lane=tid&63,r32=lane&31,hi=lane>>5; const int wid=__builtin_amdgcn_readfirstlane(tid>>6);
;   const int vlim=(vlim_in<0)?(wid>>1):vlim_in;
;   const bool act=PART?(wid<2):true;
;   const bf16*Qw=Qb+(long)(wid*QBLK)*KP;
;   const unsigned lds0=(unsigned)(uintptr_t)shm;
;   float*wsf=(float*)(shm+LDS_WS)+wid*64;
;   const bf16*ksrc=Kh+(long)lane*KP+wid*8;
;   const bf16*vsrc=Vh+(long)(16*(wid&3)+(lane>>2))*KP+(wid>>2)*32+(lane&3)*8;
;   const unsigned kdst=lds0+LDS_K+wid*1024, vdst=lds0+LDS_V+wid*1024;
;     ...
;   const int vb0=(int)(lds0+LDS_V)+((lane>>4)&1)*32+(lane&3)*8+(4*hi+((lane&15)>>2))*64;
;   const int s1=(s0==(NSLOT-1)*SLOTB)?0:s0+SLOTB, s2=(s1==(NSLOT-1)*SLOTB)?0:s1+SLOTB;
;   const char*Kbase=shm+LDS_K+s0; bf16x8 kf[8];
;   const lds_cptr shm3=(lds_cptr)shm; const lds_cptr kp0=shm3+LDS_K+hi*1024+r32*16; const lds_cptr vp0=shm3+LDS_V+((lane>>4)&1)*32+(lane&3)*8+(4*hi+((lane&15)>>2))*64;
; __global__ void __launch_bounds__(NWAVES * 64, 2) mk_fwd(Args args) {
;     ...
;             for (int i = 0; i < 8; ++i) { const int qb = (i >> 2) ? 15 - s : s, j = (i >> 1) & 1, vh = i & 1;
;                 const bf16* Qp = Qb + (size_t)(b * 4096 + qb * 256) * 512 + (hd * 2 + j) * 64; const bf16* Kp = Kb + (size_t)(b * 4096) * 512 + (hd * 2 + j) * 64; const bf16* Vp = Vb + (size_t)(b * 4096) * 512 + (hd * 2 + vh) * 64;
;                 bf16* Op = ATTO + (size_t)(b * 4096 + qb * 256) * 1024 + ((hd * 2 + j) * 2 + vh) * 64;
.LBB0_925:
	s_cmpk_gt_i32 s92, 0xff
	s_waitcnt vmcnt(0) lgkmcnt(0)
	s_barrier
	s_cbranch_scc1 .LBB0_1021
	v_mov_b32_e32 v3, 0x1a0000
	global_load_dword v217, v3, s[66:67]
	v_and_b32_e32 v0, 63, v252
	v_and_b32_e32 v1, 31, v252
	v_bfe_u32 v2, v252, 5, 1
	v_lshrrev_b32_e32 v3, 6, v252
	s_nop 0
	v_readfirstlane_b32 s4, v3
	s_and_b32 s5, s4, 3
	s_lshr_b32 s6, s4, 2
	s_mov_b32 s48, 0x41000000
	s_xor_b32 s45, s4, 2
	s_cmp_lt_u32 s4, 4
	s_cselect_b32 s45, s4, s45
	s_and_b32 s46, s45, 3
	s_lshr_b32 s47, s45, 2
	v_bfe_u32 v219, v1, 1, 3
	v_lshlrev_b32_e32 v220, 7, v1
	v_or_b32_e32 v221, 0, v2
	v_xor_b32_e32 v221, v221, v219
	v_lshl_add_u32 v235, v221, 4, v220
	v_or_b32_e32 v221, 2, v2
	v_xor_b32_e32 v221, v221, v219
	v_lshl_add_u32 v236, v221, 4, v220
	v_or_b32_e32 v221, 4, v2
	v_xor_b32_e32 v221, v221, v219
	v_lshl_add_u32 v237, v221, 4, v220
	v_or_b32_e32 v221, 6, v2
	v_xor_b32_e32 v221, v221, v219
	v_lshl_add_u32 v238, v221, 4, v220
	v_bfe_u32 v218, v0, 4, 1
	v_lshlrev_b32_e32 v229, 5, v218
	v_and_b32_e32 v218, 3, v0
	v_lshl_add_u32 v229, v218, 3, v229
	v_bfe_u32 v218, v0, 2, 2
	v_lshl_add_u32 v218, v2, 2, v218
	v_lshl_add_u32 v229, v218, 6, v229
	s_lshl_b32 s34, s4, 10
	s_add_i32 s34, s34, 0x18000
	v_mov_b32_e32 v230, s34
	v_lshlrev_b32_e32 v240, 2, v1
	v_lshlrev_b32_e32 v241, 4, v2
	v_lshrrev_b32_e32 v218, 3, v0
	s_lshl_b32 s34, s4, 3
	v_add_u32_e32 v218, s34, v218
	v_bfe_u32 v219, v218, 1, 3
	v_and_b32_e32 v220, 7, v0
	v_xor_b32_e32 v219, v219, v220
	v_lshlrev_b32_e32 v231, 10, v218
	v_lshl_add_u32 v231, v219, 4, v231
	v_lshrrev_b32_e32 v218, 2, v0
	v_lshlrev_b32_e32 v232, 10, v218
	v_and_b32_e32 v218, 3, v0
	v_lshl_add_u32 v232, v218, 4, v232
	s_lshl_b32 s34, s5, 14
	s_lshl_b32 s35, s6, 6
	s_add_i32 s34, s34, s35
	v_add_u32_e32 v232, s34, v232
	v_add_u32_e32 v233, 0x80, v232
	v_lshlrev_b32_e32 v234, 10, v1
	v_lshl_add_u32 v234, v2, 4, v234
	v_lshlrev_b32_e32 v239, 4, v0
	s_lshl_b32 s34, s92, 3
	s_add_i32 s34, s34, s4
	s_lshl_b32 s34, s34, 14
	s_add_u32 s52, s66, s34
	s_addc_u32 s53, s67, 0
	s_add_u32 s52, s52, 0x6f00000
	s_addc_u32 s53, s53, 0
	s_waitcnt vmcnt(0)
	v_readfirstlane_b32 s7, v217
	s_mov_b32 s8, s92

; template<int THRL,bool PART> __device__ __forceinline__ int attn_unit(const bf16*Qb,const bf16*__restrict__ Kh,const bf16*__restrict__ Vh,bf16*Ob,const int NT,const int vlim_in,char*shm,const int s0,const bool primed,const bf16*nKh,const bf16*nVh,bf16*fuseM,const float lam){
;     ...
;   const int vb0=(int)(lds0+LDS_V)+((lane>>4)&1)*32+(lane&3)*8+(4*hi+((lane&15)>>2))*64;
;   const int s1=(s0==(NSLOT-1)*SLOTB)?0:s0+SLOTB, s2=(s1==(NSLOT-1)*SLOTB)?0:s1+SLOTB;
;   const char*Kbase=shm+LDS_K+s0; bf16x8 kf[8];
;   const lds_cptr shm3=(lds_cptr)shm; const lds_cptr kp0=shm3+LDS_K+hi*1024+r32*16; const lds_cptr vp0=shm3+LDS_V+((lane>>4)&1)*32+(lane&3)*8+(4*hi+((lane&15)>>2))*64;
;   if(!primed){DMA_K(0,s0);DMA_V(0,s0);DMA_K(1,s1);}
;   bf16x8 qr[4];
;   #pragma unroll
;   for(int d0=0;d0<4;++d0)qr[d0]=*reinterpret_cast<const bf16x8*>(&Qw[(long)r32*KP+d0*16+hi*8]);
;   float zz_=0.f;asm volatile("":"+v"(zz_));
;   float mhat=zz_,l_reg=zz_;f32x16 o[2];
;   _Pragma("unroll") for(int r=0;r<16;++r){o[0][r]=zz_;o[1][r]=zz_;}
;   f32x16 negm;
;   _Pragma("unroll") for(int r=0;r<16;++r)negm[r]=zz_;
; __global__ void __launch_bounds__(NWAVES * 64, 2) mk_fwd(Args args) {
;     ...
;             for (int i = 0; i < 8; ++i) { const int qb = (i >> 2) ? 15 - s : s, j = (i >> 1) & 1, vh = i & 1;
;                 const bf16* Qp = Qb + (size_t)(b * 4096 + qb * 256) * 512 + (hd * 2 + j) * 64; const bf16* Kp = Kb + (size_t)(b * 4096) * 512 + (hd * 2 + j) * 64; const bf16* Vp = Vb + (size_t)(b * 4096) * 512 + (hd * 2 + vh) * 64;
;                 bf16* Op = ATTO + (size_t)(b * 4096 + qb * 256) * 1024 + ((hd * 2 + j) * 2 + vh) * 64;
;                 bf16* Mp = ((i & 3) == 3) ? H + (size_t)(b * 4096 + qb * 256) * 1024 + 512 + hd * 128 : nullptr;
;                 const bool more = i < 7; const int jn = ((i + 1) >> 1) & 1, vn = (i + 1) & 1;
;                 const bf16* nK = Kb + (size_t)(b * 4096) * 512 + (hd * 2 + jn) * 64; const bf16* nV = Vb + (size_t)(b * 4096) * 512 + (hd * 2 + vn) * 64;
;                 ring0 = attn_body::attn_unit<8, false>((const attn_body::bf16*)Qp, (const attn_body::bf16*)Kp, (const attn_body::bf16*)Vp, (attn_body::bf16*)Op, 4 * (qb + 1), -1, (char*)lds, ring0, primed,
;                                                        more ? (const attn_body::bf16*)nK : nullptr, more ? (const attn_body::bf16*)nV : nullptr, (attn_body::bf16*)Mp, lam); primed = more; }
.Lat_blk:
	s_sub_i32 s34, 15, s11
	s_cmp_eq_u32 s12, 0
	s_cselect_b32 s13, s11, s34
	s_lshl_b32 s15, s13, 2
	s_add_i32 s15, s15, 4
	s_lshr_b32 s34, s45, 1
	s_add_i32 s16, s15, s34
	s_sub_i32 s16, s16, 3
	s_mov_b32 s14, 0
.Lat_j:
	s_lshl_b32 s34, s10, 1
	s_add_i32 s34, s34, s14
	s_add_u32 s18, s66, 0xf300000
	s_addc_u32 s19, s67, 0
	s_lshl_b32 s36, s9, 22
	s_add_u32 s18, s18, s36
	s_addc_u32 s19, s19, 0
	s_lshl_b32 s36, s34, 7
	s_add_u32 s18, s18, s36
	s_addc_u32 s19, s19, 0
	s_add_u32 s20, s66, 0x12200000
	s_addc_u32 s21, s67, 0
	s_lshl_b32 s36, s9, 22
	s_add_u32 s20, s20, s36
	s_addc_u32 s21, s21, 0
	s_lshl_b32 s36, s10, 8
	s_add_u32 s20, s20, s36
	s_addc_u32 s21, s21, 0
	s_add_u32 s22, s66, 0xd100000
	s_addc_u32 s23, s67, 0
	s_lshl_b32 s36, s9, 22
	s_add_u32 s22, s22, s36
	s_addc_u32 s23, s23, 0
	s_lshl_b32 s36, s13, 18
	s_add_u32 s22, s22, s36
	s_addc_u32 s23, s23, 0
	s_lshl_b32 s36, s45, 15
	s_add_u32 s22, s22, s36
	s_addc_u32 s23, s23, 0
	s_lshl_b32 s36, s34, 7
	s_add_u32 s22, s22, s36
	s_addc_u32 s23, s23, 0
	s_mov_b32 s17, 0
	s_mov_b32 s24, 0
	global_load_dwordx4 v[4:7], v234, s[22:23]
	global_load_dwordx4 v[8:11], v234, s[22:23] offset:32
	global_load_dwordx4 v[12:15], v234, s[22:23] offset:64
	global_load_dwordx4 v[16:19], v234, s[22:23] offset:96
	s_mov_b32 s27, 0x0
	s_lshl_b32 s37, s4, 10
	s_add_i32 m0, s37, s27
	s_nop 0
	global_load_lds_dwordx4 v231, s[18:19]
	s_add_u32 s18, s18, 0x10000
	s_addc_u32 s19, s19, 0
	s_mov_b32 s27, 0x2000
	s_lshl_b32 s37, s4, 10
	s_add_i32 m0, s37, s27
	s_nop 0
	global_load_lds_dwordx4 v231, s[18:19]
	s_add_u32 s18, s18, 0x10000
	s_addc_u32 s19, s19, 0
	s_mov_b32 s27, 0x4000
	s_lshl_b32 s37, s4, 10
	s_add_i32 m0, s37, s27
	s_nop 0
	global_load_lds_dwordx4 v231, s[18:19]
	s_add_u32 s18, s18, 0x10000
	s_addc_u32 s19, s19, 0
	s_mov_b32 s27, 0x6000
	s_lshl_b32 s37, s4, 10
	s_add_i32 m0, s37, s27
	s_nop 0
	global_load_lds_dwordx4 v231, s[18:19]
	s_add_u32 s18, s18, 0x10000
	s_addc_u32 s19, s19, 0
	s_mov_b32 s29, 0x8000
	s_lshl_b32 s37, s4, 10
	s_add_i32 m0, s37, s29
	s_nop 0
	global_load_lds_dwordx4 v232, s[20:21]
	s_add_i32 m0, m0, 0x2000
	s_nop 0
	global_load_lds_dwordx4 v233, s[20:21]
	s_add_u32 s20, s20, 0x10000
	s_addc_u32 s21, s21, 0
	s_mov_b32 s29, 0xc000
	s_lshl_b32 s37, s4, 10
	s_add_i32 m0, s37, s29
	s_nop 0
	global_load_lds_dwordx4 v232, s[20:21]
	s_add_i32 m0, m0, 0x2000
	s_nop 0
	global_load_lds_dwordx4 v233, s[20:21]
	s_add_u32 s20, s20, 0x10000
	s_addc_u32 s21, s21, 0
	v_mov_b32_e32 v148, 0
	v_mov_b32_e32 v149, 0
	v_mov_b32_e32 v150, 0
	v_mov_b32_e32 v151, 0
	v_mov_b32_e32 v152, 0
	v_mov_b32_e32 v153, 0
	v_mov_b32_e32 v154, 0
	v_mov_b32_e32 v155, 0
	v_mov_b32_e32 v156, 0
	v_mov_b32_e32 v157, 0
	v_mov_b32_e32 v158, 0
	v_mov_b32_e32 v159, 0
	v_mov_b32_e32 v160, 0
	v_mov_b32_e32 v161, 0
	v_mov_b32_e32 v162, 0
	v_mov_b32_e32 v163, 0
	v_mov_b32_e32 v164, 0
	v_mov_b32_e32 v165, 0
	v_mov_b32_e32 v166, 0
	v_mov_b32_e32 v167, 0
	v_mov_b32_e32 v168, 0
	v_mov_b32_e32 v169, 0
	v_mov_b32_e32 v170, 0
	v_mov_b32_e32 v171, 0
	v_mov_b32_e32 v172, 0
	v_mov_b32_e32 v173, 0
	v_mov_b32_e32 v174, 0
	v_mov_b32_e32 v175, 0
	v_mov_b32_e32 v176, 0
	v_mov_b32_e32 v177, 0
	v_mov_b32_e32 v178, 0
	v_mov_b32_e32 v179, 0
	v_mov_b32_e32 v180, 0
	v_mov_b32_e32 v181, 0
	v_mov_b32_e32 v182, 0
	v_mov_b32_e32 v183, 0
	v_mov_b32_e32 v184, 0
	v_mov_b32_e32 v185, 0
	v_mov_b32_e32 v186, 0
	v_mov_b32_e32 v187, 0
	v_mov_b32_e32 v188, 0
	v_mov_b32_e32 v189, 0
	v_mov_b32_e32 v190, 0
	v_mov_b32_e32 v191, 0
	v_mov_b32_e32 v192, 0
	v_mov_b32_e32 v193, 0
	v_mov_b32_e32 v194, 0
	v_mov_b32_e32 v195, 0
	v_mov_b32_e32 v196, 0
	v_mov_b32_e32 v197, 0
	v_mov_b32_e32 v198, 0
	v_mov_b32_e32 v199, 0
	v_mov_b32_e32 v200, 0
	v_mov_b32_e32 v201, 0
	v_mov_b32_e32 v202, 0
	v_mov_b32_e32 v203, 0
	v_mov_b32_e32 v204, 0
	v_mov_b32_e32 v205, 0
	v_mov_b32_e32 v206, 0
	v_mov_b32_e32 v207, 0
	v_mov_b32_e32 v208, 0
	v_mov_b32_e32 v209, 0
	v_mov_b32_e32 v210, 0
	v_mov_b32_e32 v211, 0
	v_mov_b32_e32 v84, 0
	v_mov_b32_e32 v85, 0
	v_mov_b32_e32 v86, 0
	v_mov_b32_e32 v87, 0
	v_mov_b32_e32 v88, 0
	v_mov_b32_e32 v89, 0
	v_mov_b32_e32 v90, 0
	v_mov_b32_e32 v91, 0
	v_mov_b32_e32 v92, 0
	v_mov_b32_e32 v93, 0
	v_mov_b32_e32 v94, 0
	v_mov_b32_e32 v95, 0
	v_mov_b32_e32 v96, 0
	v_mov_b32_e32 v97, 0
	v_mov_b32_e32 v98, 0
	v_mov_b32_e32 v99, 0
	v_mov_b32_e32 v212, 0
	v_mov_b32_e32 v213, 0
	s_waitcnt vmcnt(0)
	s_barrier
	ds_read_b128 v[20:23], v235
	ds_read_b128 v[24:27], v236
	ds_read_b128 v[28:31], v237
	ds_read_b128 v[32:35], v238
	ds_read_b128 v[36:39], v235 offset:4096
	ds_read_b128 v[40:43], v236 offset:4096
	ds_read_b128 v[44:47], v237 offset:4096
	ds_read_b128 v[48:51], v238 offset:4096

; template<int THRL,bool PART> __device__ __forceinline__ int attn_unit(const bf16*Qb,const bf16*__restrict__ Kh,const bf16*__restrict__ Vh,bf16*Ob,const int NT,const int vlim_in,char*shm,const int s0,const bool primed,const bf16*nKh,const bf16*nVh,bf16*fuseM,const float lam){
;     ...
;     for(int i=0;i<4;++i){const int row=i*8+(lane>>3),ch=lane&7; const u32x4 v=*(const u32x4*)(stg+row*64+ch*8);
;       const bf16*gp=Ow+(long)row*OP+ch*8; const u32x4 a=*(const u32x4*)(gp-192), c1=*(const u32x4*)(gp-128), b=*(const u32x4*)(gp-64);
;       float d0[8],d1[8],ss=0.f;
;       #pragma unroll
;       for(int q=0;q<4;++q){ d0[2*q]=__uint_as_float(a[q]<<16)-lam*__uint_as_float(b[q]<<16); d0[2*q+1]=__uint_as_float(a[q]&0xffff0000u)-lam*__uint_as_float(b[q]&0xffff0000u);
;         d1[2*q]=__uint_as_float(c1[q]<<16)-lam*__uint_as_float(v[q]<<16); d1[2*q+1]=__uint_as_float(c1[q]&0xffff0000u)-lam*__uint_as_float(v[q]&0xffff0000u);
.Lat_comb11:
	v_mov_b32_e32 v219, s7
	s_waitcnt vmcnt(0)
	v_fma_f32 v20, -v219, v148, v20
	v_fma_f32 v21, -v219, v149, v21
	v_fma_f32 v22, -v219, v150, v22
	v_fma_f32 v23, -v219, v151, v23
	v_fma_f32 v24, -v219, v152, v24
	v_fma_f32 v25, -v219, v153, v25
	v_fma_f32 v26, -v219, v154, v26
	v_fma_f32 v27, -v219, v155, v27
	v_fma_f32 v28, -v219, v156, v28
	v_fma_f32 v29, -v219, v157, v29
	v_fma_f32 v30, -v219, v158, v30
	v_fma_f32 v31, -v219, v159, v31
	v_fma_f32 v32, -v219, v160, v32
	v_fma_f32 v33, -v219, v161, v33
	v_fma_f32 v34, -v219, v162, v34
	v_fma_f32 v35, -v219, v163, v35
	v_fma_f32 v36, -v219, v164, v36
	v_fma_f32 v37, -v219, v165, v37
	v_fma_f32 v38, -v219, v166, v38
	v_fma_f32 v39, -v219, v167, v39
	v_fma_f32 v40, -v219, v168, v40
	v_fma_f32 v41, -v219, v169, v41
	v_fma_f32 v42, -v219, v170, v42
	v_fma_f32 v43, -v219, v171, v43
	v_fma_f32 v44, -v219, v172, v44
	v_fma_f32 v45, -v219, v173, v45
	v_fma_f32 v46, -v219, v174, v46
	v_fma_f32 v47, -v219, v175, v47
	v_fma_f32 v48, -v219, v176, v48
	v_fma_f32 v49, -v219, v177, v49
	v_fma_f32 v50, -v219, v178, v50
	v_fma_f32 v51, -v219, v179, v51
	v_fma_f32 v52, -v219, v180, v52
	v_fma_f32 v53, -v219, v181, v53
	v_fma_f32 v54, -v219, v182, v54
	v_fma_f32 v55, -v219, v183, v55
	v_fma_f32 v56, -v219, v184, v56
	v_fma_f32 v57, -v219, v185, v57
	v_fma_f32 v58, -v219, v186, v58
	v_fma_f32 v59, -v219, v187, v59
	v_fma_f32 v60, -v219, v188, v60
	v_fma_f32 v61, -v219, v189, v61
	v_fma_f32 v62, -v219, v190, v62
	v_fma_f32 v63, -v219, v191, v63
	v_fma_f32 v64, -v219, v192, v64
	v_fma_f32 v65, -v219, v193, v65
	v_fma_f32 v66, -v219, v194, v66
	v_fma_f32 v67, -v219, v195, v67
	v_fma_f32 v68, -v219, v196, v68
	v_fma_f32 v69, -v219, v197, v69
	v_fma_f32 v70, -v219, v198, v70
	v_fma_f32 v71, -v219, v199, v71
	v_fma_f32 v72, -v219, v200, v72
	v_fma_f32 v73, -v219, v201, v73
	v_fma_f32 v74, -v219, v202, v74
	v_fma_f32 v75, -v219, v203, v75
	v_fma_f32 v76, -v219, v204, v76
	v_fma_f32 v77, -v219, v205, v77
	v_fma_f32 v78, -v219, v206, v78
	v_fma_f32 v79, -v219, v207, v79
	v_fma_f32 v80, -v219, v208, v80
	v_fma_f32 v81, -v219, v209, v81
	v_fma_f32 v82, -v219, v210, v82
	v_fma_f32 v83, -v219, v211, v83
	s_mul_i32 s34, s46, 0x4200
	v_mul_u32_u24_e32 v221, 0x840, v2
	v_add_u32_e32 v221, v221, v240
	v_add_u32_e32 v221, s34, v221
	s_add_u32 s50, s66, 0x2e00400
	s_addc_u32 s51, s67, 0
	s_lshl_b32 s36, s9, 23
	s_add_u32 s50, s50, s36
	s_addc_u32 s51, s51, 0
	s_lshl_b32 s36, s13, 19
	s_add_u32 s50, s50, s36
	s_addc_u32 s51, s51, 0
	s_lshl_b32 s36, s10, 8
	s_add_u32 s50, s50, s36
	s_addc_u32 s51, s51, 0
	s_cmp_lg_u32 s47, 0
	s_cbranch_scc1 .Lat_skipst14
	ds_write_b32 v221, v20 offset:0
	ds_write_b32 v221, v21 offset:528
	ds_write_b32 v221, v22 offset:1056
	ds_write_b32 v221, v23 offset:1584
	ds_write_b32 v221, v24 offset:4224
	ds_write_b32 v221, v25 offset:4752
	ds_write_b32 v221, v26 offset:5280
	ds_write_b32 v221, v27 offset:5808
	ds_write_b32 v221, v28 offset:8448
	ds_write_b32 v221, v29 offset:8976
	ds_write_b32 v221, v30 offset:9504
	ds_write_b32 v221, v31 offset:10032
	ds_write_b32 v221, v32 offset:12672
	ds_write_b32 v221, v33 offset:13200
	ds_write_b32 v221, v34 offset:13728
	ds_write_b32 v221, v35 offset:14256
	ds_write_b32 v221, v36 offset:128
	ds_write_b32 v221, v37 offset:656
	ds_write_b32 v221, v38 offset:1184
	ds_write_b32 v221, v39 offset:1712
	ds_write_b32 v221, v40 offset:4352
	ds_write_b32 v221, v41 offset:4880
	ds_write_b32 v221, v42 offset:5408
	ds_write_b32 v221, v43 offset:5936
	ds_write_b32 v221, v44 offset:8576
	ds_write_b32 v221, v45 offset:9104
	ds_write_b32 v221, v46 offset:9632
	ds_write_b32 v221, v47 offset:10160
	ds_write_b32 v221, v48 offset:12800
	ds_write_b32 v221, v49 offset:13328
	ds_write_b32 v221, v50 offset:13856
	ds_write_b32 v221, v51 offset:14384
	ds_write_b32 v221, v52 offset:256
	ds_write_b32 v221, v53 offset:784
	ds_write_b32 v221, v54 offset:1312
	ds_write_b32 v221, v55 offset:1840
	ds_write_b32 v221, v56 offset:4480
	ds_write_b32 v221, v57 offset:5008
	ds_write_b32 v221, v58 offset:5536
	ds_write_b32 v221, v59 offset:6064
	ds_write_b32 v221, v60 offset:8704
	ds_write_b32 v221, v61 offset:9232
	ds_write_b32 v221, v62 offset:9760
	ds_write_b32 v221, v63 offset:10288
	ds_write_b32 v221, v64 offset:12928
	ds_write_b32 v221, v65 offset:13456
	ds_write_b32 v221, v66 offset:13984
	ds_write_b32 v221, v67 offset:14512
	ds_write_b32 v221, v68 offset:384
	ds_write_b32 v221, v69 offset:912
	ds_write_b32 v221, v70 offset:1440
	ds_write_b32 v221, v71 offset:1968
	ds_write_b32 v221, v72 offset:4608
	ds_write_b32 v221, v73 offset:5136
	ds_write_b32 v221, v74 offset:5664
	ds_write_b32 v221, v75 offset:6192
	ds_write_b32 v221, v76 offset:8832
	ds_write_b32 v221, v77 offset:9360
	ds_write_b32 v221, v78 offset:9888
	ds_write_b32 v221, v79 offset:10416
	ds_write_b32 v221, v80 offset:13056
	ds_write_b32 v221, v81 offset:13584
	ds_write_b32 v221, v82 offset:14112
	ds_write_b32 v221, v83 offset:14640
; __device__ __forceinline__ unsigned cvtpk_s(float lo,float hi){f32x2_t v={lo,hi};bf16x2_t b=__builtin_convertvector(v,bf16x2_t);return __builtin_bit_cast(unsigned,b);}
; template<int THRL,bool PART> __device__ __forceinline__ int attn_unit(const bf16*Qb,const bf16*__restrict__ Kh,const bf16*__restrict__ Vh,bf16*Ob,const int NT,const int vlim_in,char*shm,const int s0,const bool primed,const bf16*nKh,const bf16*nVh,bf16*fuseM,const float lam){
;     ...
;     for(int i=0;i<4;++i){const int row=i*8+(lane>>3),ch=lane&7; const u32x4 v=*(const u32x4*)(stg+row*64+ch*8);
;       const bf16*gp=Ow+(long)row*OP+ch*8; const u32x4 a=*(const u32x4*)(gp-192), c1=*(const u32x4*)(gp-128), b=*(const u32x4*)(gp-64);
;       float d0[8],d1[8],ss=0.f;
;       #pragma unroll
;       for(int q=0;q<4;++q){ d0[2*q]=__uint_as_float(a[q]<<16)-lam*__uint_as_float(b[q]<<16); d0[2*q+1]=__uint_as_float(a[q]&0xffff0000u)-lam*__uint_as_float(b[q]&0xffff0000u);
;         d1[2*q]=__uint_as_float(c1[q]<<16)-lam*__uint_as_float(v[q]<<16); d1[2*q+1]=__uint_as_float(c1[q]&0xffff0000u)-lam*__uint_as_float(v[q]&0xffff0000u);
;         ss+=d0[2*q]*d0[2*q]+d0[2*q+1]*d0[2*q+1]+d1[2*q]*d1[2*q]+d1[2*q+1]*d1[2*q+1]; }
;       ss+=__shfl_xor(ss,1); ss+=__shfl_xor(ss,2); ss+=__shfl_xor(ss,4);
;       const float rn=rsqrtf(ss*(1.0f/128.0f)+1e-6f)*0.8f;
;       u32x4 w0,w1;
;       #pragma unroll
;       for(int q=0;q<4;++q){ w0[q]=cvtpk_s(d0[2*q]*rn,d0[2*q+1]*rn); w1[q]=cvtpk_s(d1[2*q]*rn,d1[2*q+1]*rn); }
;       *(u32x4*)(Mw+(long)row*OP+ch*8)=w0; *(u32x4*)(Mw+(long)row*OP+64+ch*8)=w1; }
.Lat_skipst14:
	s_waitcnt lgkmcnt(0)
	s_barrier
	v_lshrrev_b32_e32 v223, 2, v252
	v_and_b32_e32 v224, 3, v252
	v_mul_u32_u24_e32 v222, 0x210, v223
	v_lshl_add_u32 v222, v224, 7, v222
	ds_read_b128 v[100:103], v222 offset:0
	ds_read_b128 v[104:107], v222 offset:16
	ds_read_b128 v[108:111], v222 offset:32
	ds_read_b128 v[112:115], v222 offset:48
	ds_read_b128 v[116:119], v222 offset:64
	ds_read_b128 v[120:123], v222 offset:80
	ds_read_b128 v[124:127], v222 offset:96
	ds_read_b128 v[128:131], v222 offset:112
	s_waitcnt lgkmcnt(0)
	v_mul_f32_e32 v219, v100, v100
	v_fmac_f32_e32 v219, v101, v101
	v_fmac_f32_e32 v219, v102, v102
	v_fmac_f32_e32 v219, v103, v103
	v_fmac_f32_e32 v219, v104, v104
	v_fmac_f32_e32 v219, v105, v105
	v_fmac_f32_e32 v219, v106, v106
	v_fmac_f32_e32 v219, v107, v107
	v_fmac_f32_e32 v219, v108, v108
	v_fmac_f32_e32 v219, v109, v109
	v_fmac_f32_e32 v219, v110, v110
	v_fmac_f32_e32 v219, v111, v111
	v_fmac_f32_e32 v219, v112, v112
	v_fmac_f32_e32 v219, v113, v113
	v_fmac_f32_e32 v219, v114, v114
	v_fmac_f32_e32 v219, v115, v115
	v_fmac_f32_e32 v219, v116, v116
	v_fmac_f32_e32 v219, v117, v117
	v_fmac_f32_e32 v219, v118, v118
	v_fmac_f32_e32 v219, v119, v119
	v_fmac_f32_e32 v219, v120, v120
	v_fmac_f32_e32 v219, v121, v121
	v_fmac_f32_e32 v219, v122, v122
	v_fmac_f32_e32 v219, v123, v123
	v_fmac_f32_e32 v219, v124, v124
	v_fmac_f32_e32 v219, v125, v125
	v_fmac_f32_e32 v219, v126, v126
	v_fmac_f32_e32 v219, v127, v127
	v_fmac_f32_e32 v219, v128, v128
	v_fmac_f32_e32 v219, v129, v129
	v_fmac_f32_e32 v219, v130, v130
	v_fmac_f32_e32 v219, v131, v131
	s_nop 1
	v_add_f32_dpp v219, v219, v219 quad_perm:[1,0,3,2] row_mask:0xf bank_mask:0xf
	s_nop 1
	v_add_f32_dpp v219, v219, v219 quad_perm:[2,3,0,1] row_mask:0xf bank_mask:0xf
	v_mov_b32_e32 v220, 0x358637bd
	v_fmamk_f32 v219, v219, 0x3c000000, v220
	v_rsq_f32_e32 v219, v219
	s_nop 0
	v_mul_f32_e32 v219, 0x3f4ccccd, v219
	v_mul_f32_e32 v100, v100, v219
	v_mul_f32_e32 v101, v101, v219
	v_mul_f32_e32 v102, v102, v219
	v_mul_f32_e32 v103, v103, v219
	v_mul_f32_e32 v104, v104, v219
	v_mul_f32_e32 v105, v105, v219
	v_mul_f32_e32 v106, v106, v219
	v_mul_f32_e32 v107, v107, v219
	v_mul_f32_e32 v108, v108, v219
	v_mul_f32_e32 v109, v109, v219
	v_mul_f32_e32 v110, v110, v219
	v_mul_f32_e32 v111, v111, v219
	v_mul_f32_e32 v112, v112, v219
	v_mul_f32_e32 v113, v113, v219
	v_mul_f32_e32 v114, v114, v219
	v_mul_f32_e32 v115, v115, v219
	v_mul_f32_e32 v116, v116, v219
	v_mul_f32_e32 v117, v117, v219
	v_mul_f32_e32 v118, v118, v219
	v_mul_f32_e32 v119, v119, v219
	v_mul_f32_e32 v120, v120, v219
	v_mul_f32_e32 v121, v121, v219
	v_mul_f32_e32 v122, v122, v219
	v_mul_f32_e32 v123, v123, v219
	v_mul_f32_e32 v124, v124, v219
	v_mul_f32_e32 v125, v125, v219
	v_mul_f32_e32 v126, v126, v219
	v_mul_f32_e32 v127, v127, v219
	v_mul_f32_e32 v128, v128, v219
	v_mul_f32_e32 v129, v129, v219
	v_mul_f32_e32 v130, v130, v219
	v_mul_f32_e32 v131, v131, v219
	v_cvt_pk_bf16_f32 v132, v100, v101
	v_cvt_pk_bf16_f32 v133, v102, v103
	v_cvt_pk_bf16_f32 v134, v104, v105
	v_cvt_pk_bf16_f32 v135, v106, v107
	v_cvt_pk_bf16_f32 v136, v108, v109
	v_cvt_pk_bf16_f32 v137, v110, v111
	v_cvt_pk_bf16_f32 v138, v112, v113
	v_cvt_pk_bf16_f32 v139, v114, v115
	v_cvt_pk_bf16_f32 v140, v116, v117
	v_cvt_pk_bf16_f32 v141, v118, v119
	v_cvt_pk_bf16_f32 v142, v120, v121
	v_cvt_pk_bf16_f32 v143, v122, v123
	v_cvt_pk_bf16_f32 v144, v124, v125
	v_cvt_pk_bf16_f32 v145, v126, v127
	v_cvt_pk_bf16_f32 v146, v128, v129
	v_cvt_pk_bf16_f32 v147, v130, v131
	v_lshlrev_b32_e32 v222, 11, v223
	v_lshl_add_u32 v222, v224, 6, v222
	global_store_dwordx4 v222, v[132:135], s[50:51]
	global_store_dwordx4 v222, v[136:139], s[50:51] offset:16
	global_store_dwordx4 v222, v[140:143], s[50:51] offset:32
	global_store_dwordx4 v222, v[144:147], s[50:51] offset:48
	s_barrier
	s_cmp_lg_u32 s47, 1
	s_cbranch_scc1 .Lat_skipst15
	ds_write_b32 v221, v20 offset:0
	ds_write_b32 v221, v21 offset:528
	ds_write_b32 v221, v22 offset:1056
	ds_write_b32 v221, v23 offset:1584
	ds_write_b32 v221, v24 offset:4224
	ds_write_b32 v221, v25 offset:4752
	ds_write_b32 v221, v26 offset:5280
	ds_write_b32 v221, v27 offset:5808
	ds_write_b32 v221, v28 offset:8448
	ds_write_b32 v221, v29 offset:8976
	ds_write_b32 v221, v30 offset:9504
	ds_write_b32 v221, v31 offset:10032
	ds_write_b32 v221, v32 offset:12672
	ds_write_b32 v221, v33 offset:13200
	ds_write_b32 v221, v34 offset:13728
	ds_write_b32 v221, v35 offset:14256
	ds_write_b32 v221, v36 offset:128
	ds_write_b32 v221, v37 offset:656
	ds_write_b32 v221, v38 offset:1184
	ds_write_b32 v221, v39 offset:1712
	ds_write_b32 v221, v40 offset:4352
	ds_write_b32 v221, v41 offset:4880
	ds_write_b32 v221, v42 offset:5408
	ds_write_b32 v221, v43 offset:5936
	ds_write_b32 v221, v44 offset:8576
	ds_write_b32 v221, v45 offset:9104
	ds_write_b32 v221, v46 offset:9632
	ds_write_b32 v221, v47 offset:10160
	ds_write_b32 v221, v48 offset:12800
	ds_write_b32 v221, v49 offset:13328
	ds_write_b32 v221, v50 offset:13856
	ds_write_b32 v221, v51 offset:14384
	ds_write_b32 v221, v52 offset:256
	ds_write_b32 v221, v53 offset:784
	ds_write_b32 v221, v54 offset:1312
	ds_write_b32 v221, v55 offset:1840
	ds_write_b32 v221, v56 offset:4480
	ds_write_b32 v221, v57 offset:5008
	ds_write_b32 v221, v58 offset:5536
	ds_write_b32 v221, v59 offset:6064
	ds_write_b32 v221, v60 offset:8704
	ds_write_b32 v221, v61 offset:9232
	ds_write_b32 v221, v62 offset:9760
	ds_write_b32 v221, v63 offset:10288
	ds_write_b32 v221, v64 offset:12928
	ds_write_b32 v221, v65 offset:13456
	ds_write_b32 v221, v66 offset:13984
	ds_write_b32 v221, v67 offset:14512
	ds_write_b32 v221, v68 offset:384
	ds_write_b32 v221, v69 offset:912
	ds_write_b32 v221, v70 offset:1440
	ds_write_b32 v221, v71 offset:1968
	ds_write_b32 v221, v72 offset:4608
	ds_write_b32 v221, v73 offset:5136
	ds_write_b32 v221, v74 offset:5664
	ds_write_b32 v221, v75 offset:6192
	ds_write_b32 v221, v76 offset:8832
	ds_write_b32 v221, v77 offset:9360
	ds_write_b32 v221, v78 offset:9888
	ds_write_b32 v221, v79 offset:10416
	ds_write_b32 v221, v80 offset:13056
	ds_write_b32 v221, v81 offset:13584
	ds_write_b32 v221, v82 offset:14112
	ds_write_b32 v221, v83 offset:14640
